# nt on the P4b fast path's SIDE record loads (read-once)
# baseline (speedup 1.0000x reference)
.LBB0_653:
	s_or_b64 exec, exec, s[6:7]
	v_lshl_add_u32 v24, s33, 9, v172
	s_mov_b32 s2, 0xb0000
	v_cmp_gt_i32_e32 vcc, s2, v24
	s_waitcnt lgkmcnt(0)
	s_barrier
	s_and_saveexec_b64 s[6:7], vcc
	s_cbranch_execz .LBB0_666
	s_cmp_eq_u32 s3, 0x100
	s_cbranch_scc0 .Lp4b_generic
	s_load_dwordx2 s[10:11], s[0:1], 0xb0
	s_load_dwordx2 s[8:9], s[0:1], 0x70
	s_mov_b32 s22, 0x2e8ba2e9
	s_mov_b32 s12, 0x3dd2d3e8
	s_movk_i32 s23, 0x2c00
	s_mov_b32 s24, 0x10000
	v_mov_b32_e32 v16, 0xc0135761
	s_waitcnt lgkmcnt(0)
	s_add_u32 s14, s10, 0x6800000
	s_addc_u32 s15, s11, 0
	s_add_u32 s16, s14, 0x2c00
	s_addc_u32 s17, s15, 0
	s_add_u32 s18, s10, 0x12800000
	s_addc_u32 s19, s11, 0
	v_mov_b32_e32 v0, v24
	v_mul_hi_u32 v1, v0, s22
	v_lshrrev_b32_e32 v1, 7, v1
	v_mul_u32_u24_e32 v2, 0x2c0, v1
	v_sub_u32_e32 v3, v0, v2
	v_lshlrev_b32_e32 v4, 4, v3
	v_mul_u32_u24_e32 v5, 3, v1
	v_mad_u32_u24 v6, v5, s23, v4
	v_and_b32_e32 v7, 1, v1
	v_lshrrev_b32_e32 v8, 1, v1
	v_add_u32_e32 v10, v8, v7
	v_and_b32_e32 v10, 31, v10
	v_cmp_ne_u32_e32 vcc, 0, v10
	v_mul_u32_u24_e32 v9, 0x10800, v7
	v_add_u32_e32 v9, 0xffffd400, v9
	v_mul_u32_u24_e32 v11, 0x5800, v7
	v_cndmask_b32_e32 v9, 0, v9, vcc
	v_cndmask_b32_e64 v50, 0, 1.0, vcc
	v_add_u32_e32 v9, v6, v9
	v_add_u32_e32 v11, v11, v4
	v_lshlrev_b32_e32 v12, 6, v8
	v_mad_u32_u24 v12, v7, 63, v12
	v_mul_u32_u24_e32 v13, 0x1600, v12
	v_lshrrev_b32_e32 v14, 1, v4
	v_add_u32_e32 v48, v13, v14
	global_load_dwordx4 v[32:35], v6, s[14:15] nt
	global_load_dwordx4 v[36:39], v6, s[16:17] nt
	global_load_dwordx4 v[40:43], v9, s[14:15] nt
	global_load_dwordx4 v[44:47], v11, s[8:9]
	v_add_u32_e32 v0, 0x20000, v24
	v_mul_hi_u32 v1, v0, s22
	v_lshrrev_b32_e32 v1, 7, v1
	v_mul_u32_u24_e32 v2, 0x2c0, v1
	v_sub_u32_e32 v3, v0, v2
	v_lshlrev_b32_e32 v4, 4, v3
	v_mul_u32_u24_e32 v5, 3, v1
	v_mad_u32_u24 v6, v5, s23, v4
	v_and_b32_e32 v7, 1, v1
	v_lshrrev_b32_e32 v8, 1, v1
	v_add_u32_e32 v10, v8, v7
	v_and_b32_e32 v10, 31, v10
	v_cmp_ne_u32_e32 vcc, 0, v10
	v_mul_u32_u24_e32 v9, 0x10800, v7
	v_add_u32_e32 v9, 0xffffd400, v9
	v_mul_u32_u24_e32 v11, 0x5800, v7
	v_cndmask_b32_e32 v9, 0, v9, vcc
	v_cndmask_b32_e64 v70, 0, 1.0, vcc
	v_add_u32_e32 v9, v6, v9
	v_add_u32_e32 v11, v11, v4
	v_lshlrev_b32_e32 v12, 6, v8
	v_mad_u32_u24 v12, v7, 63, v12
	v_mul_u32_u24_e32 v13, 0x1600, v12
	v_lshrrev_b32_e32 v14, 1, v4
	v_add_u32_e32 v68, v13, v14
	global_load_dwordx4 v[52:55], v6, s[14:15] nt
	global_load_dwordx4 v[56:59], v6, s[16:17] nt
	global_load_dwordx4 v[60:63], v9, s[14:15] nt
	global_load_dwordx4 v[64:67], v11, s[8:9]
	v_add_u32_e32 v0, 0x40000, v24
	v_mul_hi_u32 v1, v0, s22
	v_lshrrev_b32_e32 v1, 7, v1
	v_mul_u32_u24_e32 v2, 0x2c0, v1
	v_sub_u32_e32 v3, v0, v2
	v_lshlrev_b32_e32 v4, 4, v3
	v_mul_u32_u24_e32 v5, 3, v1
	v_mad_u32_u24 v6, v5, s23, v4
	v_and_b32_e32 v7, 1, v1
	v_lshrrev_b32_e32 v8, 1, v1
	v_add_u32_e32 v10, v8, v7
	v_and_b32_e32 v10, 31, v10
	v_cmp_ne_u32_e32 vcc, 0, v10
	v_mul_u32_u24_e32 v9, 0x10800, v7
	v_add_u32_e32 v9, 0xffffd400, v9
	v_mul_u32_u24_e32 v11, 0x5800, v7
	v_cndmask_b32_e32 v9, 0, v9, vcc
	v_cndmask_b32_e64 v90, 0, 1.0, vcc
	v_add_u32_e32 v9, v6, v9
	v_add_u32_e32 v11, v11, v4
	v_lshlrev_b32_e32 v12, 6, v8
	v_mad_u32_u24 v12, v7, 63, v12
	v_mul_u32_u24_e32 v13, 0x1600, v12
	v_lshrrev_b32_e32 v14, 1, v4
	v_add_u32_e32 v88, v13, v14
	global_load_dwordx4 v[72:75], v6, s[14:15] nt
	global_load_dwordx4 v[76:79], v6, s[16:17] nt
	global_load_dwordx4 v[80:83], v9, s[14:15] nt
	global_load_dwordx4 v[84:87], v11, s[8:9]
	v_add_u32_e32 v0, 0x60000, v24
	v_mul_hi_u32 v1, v0, s22
	v_lshrrev_b32_e32 v1, 7, v1
	v_mul_u32_u24_e32 v2, 0x2c0, v1
	v_sub_u32_e32 v3, v0, v2
	v_lshlrev_b32_e32 v4, 4, v3
	v_mul_u32_u24_e32 v5, 3, v1
	v_mad_u32_u24 v6, v5, s23, v4
	v_and_b32_e32 v7, 1, v1
	v_lshrrev_b32_e32 v8, 1, v1
	v_add_u32_e32 v10, v8, v7
	v_and_b32_e32 v10, 31, v10
	v_cmp_ne_u32_e32 vcc, 0, v10
	v_mul_u32_u24_e32 v9, 0x10800, v7
	v_add_u32_e32 v9, 0xffffd400, v9
	v_mul_u32_u24_e32 v11, 0x5800, v7
	v_cndmask_b32_e32 v9, 0, v9, vcc
	v_cndmask_b32_e64 v110, 0, 1.0, vcc
	v_add_u32_e32 v9, v6, v9
	v_add_u32_e32 v11, v11, v4
	v_lshlrev_b32_e32 v12, 6, v8
	v_mad_u32_u24 v12, v7, 63, v12
	v_mul_u32_u24_e32 v13, 0x1600, v12
	v_lshrrev_b32_e32 v14, 1, v4
	v_add_u32_e32 v108, v13, v14
	global_load_dwordx4 v[92:95], v6, s[14:15] nt
	global_load_dwordx4 v[96:99], v6, s[16:17] nt
	global_load_dwordx4 v[100:103], v9, s[14:15] nt
	global_load_dwordx4 v[104:107], v11, s[8:9]
	v_add_u32_e32 v0, 0x80000, v24
	v_mul_hi_u32 v1, v0, s22
	v_lshrrev_b32_e32 v1, 7, v1
	v_mul_u32_u24_e32 v2, 0x2c0, v1
	v_sub_u32_e32 v3, v0, v2
	v_lshlrev_b32_e32 v4, 4, v3
	v_mul_u32_u24_e32 v5, 3, v1
	v_mad_u32_u24 v6, v5, s23, v4
	v_and_b32_e32 v7, 1, v1
	v_lshrrev_b32_e32 v8, 1, v1
	v_add_u32_e32 v10, v8, v7
	v_and_b32_e32 v10, 31, v10
	v_cmp_ne_u32_e32 vcc, 0, v10
	v_mul_u32_u24_e32 v9, 0x10800, v7
	v_add_u32_e32 v9, 0xffffd400, v9
	v_mul_u32_u24_e32 v11, 0x5800, v7
	v_cndmask_b32_e32 v9, 0, v9, vcc
	v_cndmask_b32_e64 v130, 0, 1.0, vcc
	v_add_u32_e32 v9, v6, v9
	v_add_u32_e32 v11, v11, v4
	v_lshlrev_b32_e32 v12, 6, v8
	v_mad_u32_u24 v12, v7, 63, v12
	v_mul_u32_u24_e32 v13, 0x1600, v12
	v_lshrrev_b32_e32 v14, 1, v4
	v_add_u32_e32 v128, v13, v14
	global_load_dwordx4 v[112:115], v6, s[14:15] nt
	global_load_dwordx4 v[116:119], v6, s[16:17] nt
	global_load_dwordx4 v[120:123], v9, s[14:15] nt
	global_load_dwordx4 v[124:127], v11, s[8:9]
	v_add_u32_e32 v0, 0xa0000, v24
	v_cmp_gt_u32_e32 vcc, s24, v24
	s_nop 1
	v_cndmask_b32_e32 v0, v24, v0, vcc
	v_mul_hi_u32 v1, v0, s22
	v_lshrrev_b32_e32 v1, 7, v1
	v_mul_u32_u24_e32 v2, 0x2c0, v1
	v_sub_u32_e32 v3, v0, v2
	v_lshlrev_b32_e32 v4, 4, v3
	v_mul_u32_u24_e32 v5, 3, v1
	v_mad_u32_u24 v6, v5, s23, v4
	v_and_b32_e32 v7, 1, v1
	v_lshrrev_b32_e32 v8, 1, v1
	v_add_u32_e32 v10, v8, v7
	v_and_b32_e32 v10, 31, v10
	v_cmp_ne_u32_e32 vcc, 0, v10
	v_mul_u32_u24_e32 v9, 0x10800, v7
	v_add_u32_e32 v9, 0xffffd400, v9
	v_mul_u32_u24_e32 v11, 0x5800, v7
	v_cndmask_b32_e32 v9, 0, v9, vcc
	v_cndmask_b32_e64 v150, 0, 1.0, vcc
	v_add_u32_e32 v9, v6, v9
	v_add_u32_e32 v11, v11, v4
	v_lshlrev_b32_e32 v12, 6, v8
	v_mad_u32_u24 v12, v7, 63, v12
	v_mul_u32_u24_e32 v13, 0x1600, v12
	v_lshrrev_b32_e32 v14, 1, v4
	v_add_u32_e32 v148, v13, v14
	global_load_dwordx4 v[132:135], v6, s[14:15] nt
	global_load_dwordx4 v[136:139], v6, s[16:17] nt
	global_load_dwordx4 v[140:143], v9, s[14:15] nt
	global_load_dwordx4 v[144:147], v11, s[8:9]
	s_waitcnt vmcnt(20)
	v_pk_mul_f32 v[44:45], v[44:45], v[50:51] op_sel_hi:[1,0]
	v_pk_mul_f32 v[46:47], v[46:47], v[50:51] op_sel_hi:[1,0]
	v_pk_fma_f32 v[4:5], v[40:41], v[44:45], v[32:33]
	v_pk_fma_f32 v[6:7], v[42:43], v[46:47], v[34:35]
	v_pk_mul_f32 v[10:11], v[4:5], v[4:5]
	v_pk_mul_f32 v[8:9], v[6:7], v[6:7]
	v_pk_fma_f32 v[10:11], v[10:11], s[12:13], v[16:17] op_sel_hi:[1,0,0] neg_lo:[1,0,0] neg_hi:[1,0,0]
	v_pk_fma_f32 v[8:9], v[8:9], s[12:13], v[16:17] op_sel_hi:[1,0,0] neg_lo:[1,0,0] neg_hi:[1,0,0]
	v_pk_mul_f32 v[10:11], v[4:5], v[10:11]
	v_pk_mul_f32 v[8:9], v[6:7], v[8:9]
	v_exp_f32_e32 v10, v10
	v_exp_f32_e32 v11, v11
	v_exp_f32_e32 v8, v8
	v_exp_f32_e32 v9, v9
	s_nop 0
	v_pk_add_f32 v[10:11], v[10:11], 1.0 op_sel_hi:[1,0]
	v_pk_add_f32 v[8:9], v[8:9], 1.0 op_sel_hi:[1,0]
	v_rcp_f32_e32 v10, v10
	v_rcp_f32_e32 v11, v11
	v_rcp_f32_e32 v8, v8
	v_rcp_f32_e32 v9, v9
	s_nop 0
	v_pk_mul_f32 v[4:5], v[4:5], v[10:11]
	v_pk_mul_f32 v[6:7], v[6:7], v[8:9]
	v_pk_mul_f32 v[0:1], v[36:37], v[4:5]
	v_pk_mul_f32 v[2:3], v[38:39], v[6:7]
	s_nop 0
	v_cvt_pk_bf16_f32 v0, v0, v1
	v_cvt_pk_bf16_f32 v1, v2, v3
	s_nop 0
	global_store_dwordx2 v48, v[0:1], s[18:19]
	s_waitcnt vmcnt(17)
	v_pk_mul_f32 v[64:65], v[64:65], v[70:71] op_sel_hi:[1,0]
	v_pk_mul_f32 v[66:67], v[66:67], v[70:71] op_sel_hi:[1,0]
	v_pk_fma_f32 v[4:5], v[60:61], v[64:65], v[52:53]
	v_pk_fma_f32 v[6:7], v[62:63], v[66:67], v[54:55]
	v_pk_mul_f32 v[10:11], v[4:5], v[4:5]
	v_pk_mul_f32 v[8:9], v[6:7], v[6:7]
	v_pk_fma_f32 v[10:11], v[10:11], s[12:13], v[16:17] op_sel_hi:[1,0,0] neg_lo:[1,0,0] neg_hi:[1,0,0]
	v_pk_fma_f32 v[8:9], v[8:9], s[12:13], v[16:17] op_sel_hi:[1,0,0] neg_lo:[1,0,0] neg_hi:[1,0,0]
	v_pk_mul_f32 v[10:11], v[4:5], v[10:11]
	v_pk_mul_f32 v[8:9], v[6:7], v[8:9]
	v_exp_f32_e32 v10, v10
	v_exp_f32_e32 v11, v11
	v_exp_f32_e32 v8, v8
	v_exp_f32_e32 v9, v9
	s_nop 0
	v_pk_add_f32 v[10:11], v[10:11], 1.0 op_sel_hi:[1,0]
	v_pk_add_f32 v[8:9], v[8:9], 1.0 op_sel_hi:[1,0]
	v_rcp_f32_e32 v10, v10
	v_rcp_f32_e32 v11, v11
	v_rcp_f32_e32 v8, v8
	v_rcp_f32_e32 v9, v9
	s_nop 0
	v_pk_mul_f32 v[4:5], v[4:5], v[10:11]
	v_pk_mul_f32 v[6:7], v[6:7], v[8:9]
	v_pk_mul_f32 v[0:1], v[56:57], v[4:5]
	v_pk_mul_f32 v[2:3], v[58:59], v[6:7]
	s_nop 0
	v_cvt_pk_bf16_f32 v0, v0, v1
	v_cvt_pk_bf16_f32 v1, v2, v3
	s_nop 0
	global_store_dwordx2 v68, v[0:1], s[18:19]
	s_waitcnt vmcnt(14)
	v_pk_mul_f32 v[84:85], v[84:85], v[90:91] op_sel_hi:[1,0]
	v_pk_mul_f32 v[86:87], v[86:87], v[90:91] op_sel_hi:[1,0]
	v_pk_fma_f32 v[4:5], v[80:81], v[84:85], v[72:73]
	v_pk_fma_f32 v[6:7], v[82:83], v[86:87], v[74:75]
	v_pk_mul_f32 v[10:11], v[4:5], v[4:5]
	v_pk_mul_f32 v[8:9], v[6:7], v[6:7]
	v_pk_fma_f32 v[10:11], v[10:11], s[12:13], v[16:17] op_sel_hi:[1,0,0] neg_lo:[1,0,0] neg_hi:[1,0,0]
	v_pk_fma_f32 v[8:9], v[8:9], s[12:13], v[16:17] op_sel_hi:[1,0,0] neg_lo:[1,0,0] neg_hi:[1,0,0]
	v_pk_mul_f32 v[10:11], v[4:5], v[10:11]
	v_pk_mul_f32 v[8:9], v[6:7], v[8:9]
	v_exp_f32_e32 v10, v10
	v_exp_f32_e32 v11, v11
	v_exp_f32_e32 v8, v8
	v_exp_f32_e32 v9, v9
	s_nop 0
	v_pk_add_f32 v[10:11], v[10:11], 1.0 op_sel_hi:[1,0]
	v_pk_add_f32 v[8:9], v[8:9], 1.0 op_sel_hi:[1,0]
	v_rcp_f32_e32 v10, v10
	v_rcp_f32_e32 v11, v11
	v_rcp_f32_e32 v8, v8
	v_rcp_f32_e32 v9, v9
	s_nop 0
	v_pk_mul_f32 v[4:5], v[4:5], v[10:11]
	v_pk_mul_f32 v[6:7], v[6:7], v[8:9]
	v_pk_mul_f32 v[0:1], v[76:77], v[4:5]
	v_pk_mul_f32 v[2:3], v[78:79], v[6:7]
	s_nop 0
	v_cvt_pk_bf16_f32 v0, v0, v1
	v_cvt_pk_bf16_f32 v1, v2, v3
	s_nop 0
	global_store_dwordx2 v88, v[0:1], s[18:19]
	s_waitcnt vmcnt(11)
	v_pk_mul_f32 v[104:105], v[104:105], v[110:111] op_sel_hi:[1,0]
	v_pk_mul_f32 v[106:107], v[106:107], v[110:111] op_sel_hi:[1,0]
	v_pk_fma_f32 v[4:5], v[100:101], v[104:105], v[92:93]
	v_pk_fma_f32 v[6:7], v[102:103], v[106:107], v[94:95]
	v_pk_mul_f32 v[10:11], v[4:5], v[4:5]
	v_pk_mul_f32 v[8:9], v[6:7], v[6:7]
	v_pk_fma_f32 v[10:11], v[10:11], s[12:13], v[16:17] op_sel_hi:[1,0,0] neg_lo:[1,0,0] neg_hi:[1,0,0]
	v_pk_fma_f32 v[8:9], v[8:9], s[12:13], v[16:17] op_sel_hi:[1,0,0] neg_lo:[1,0,0] neg_hi:[1,0,0]
	v_pk_mul_f32 v[10:11], v[4:5], v[10:11]
	v_pk_mul_f32 v[8:9], v[6:7], v[8:9]
	v_exp_f32_e32 v10, v10
	v_exp_f32_e32 v11, v11
	v_exp_f32_e32 v8, v8
	v_exp_f32_e32 v9, v9
	s_nop 0
	v_pk_add_f32 v[10:11], v[10:11], 1.0 op_sel_hi:[1,0]
	v_pk_add_f32 v[8:9], v[8:9], 1.0 op_sel_hi:[1,0]
	v_rcp_f32_e32 v10, v10
	v_rcp_f32_e32 v11, v11
	v_rcp_f32_e32 v8, v8
	v_rcp_f32_e32 v9, v9
	s_nop 0
	v_pk_mul_f32 v[4:5], v[4:5], v[10:11]
	v_pk_mul_f32 v[6:7], v[6:7], v[8:9]
	v_pk_mul_f32 v[0:1], v[96:97], v[4:5]
	v_pk_mul_f32 v[2:3], v[98:99], v[6:7]
	s_nop 0
	v_cvt_pk_bf16_f32 v0, v0, v1
	v_cvt_pk_bf16_f32 v1, v2, v3
	s_nop 0
	global_store_dwordx2 v108, v[0:1], s[18:19]
	s_waitcnt vmcnt(8)
	v_pk_mul_f32 v[124:125], v[124:125], v[130:131] op_sel_hi:[1,0]
	v_pk_mul_f32 v[126:127], v[126:127], v[130:131] op_sel_hi:[1,0]
	v_pk_fma_f32 v[4:5], v[120:121], v[124:125], v[112:113]
	v_pk_fma_f32 v[6:7], v[122:123], v[126:127], v[114:115]
	v_pk_mul_f32 v[10:11], v[4:5], v[4:5]
	v_pk_mul_f32 v[8:9], v[6:7], v[6:7]
	v_pk_fma_f32 v[10:11], v[10:11], s[12:13], v[16:17] op_sel_hi:[1,0,0] neg_lo:[1,0,0] neg_hi:[1,0,0]
	v_pk_fma_f32 v[8:9], v[8:9], s[12:13], v[16:17] op_sel_hi:[1,0,0] neg_lo:[1,0,0] neg_hi:[1,0,0]
	v_pk_mul_f32 v[10:11], v[4:5], v[10:11]
	v_pk_mul_f32 v[8:9], v[6:7], v[8:9]
	v_exp_f32_e32 v10, v10
	v_exp_f32_e32 v11, v11
	v_exp_f32_e32 v8, v8
	v_exp_f32_e32 v9, v9
	s_nop 0
	v_pk_add_f32 v[10:11], v[10:11], 1.0 op_sel_hi:[1,0]
	v_pk_add_f32 v[8:9], v[8:9], 1.0 op_sel_hi:[1,0]
	v_rcp_f32_e32 v10, v10
	v_rcp_f32_e32 v11, v11
	v_rcp_f32_e32 v8, v8
	v_rcp_f32_e32 v9, v9
	s_nop 0
	v_pk_mul_f32 v[4:5], v[4:5], v[10:11]
	v_pk_mul_f32 v[6:7], v[6:7], v[8:9]
	v_pk_mul_f32 v[0:1], v[116:117], v[4:5]
	v_pk_mul_f32 v[2:3], v[118:119], v[6:7]
	s_nop 0
	v_cvt_pk_bf16_f32 v0, v0, v1
	v_cvt_pk_bf16_f32 v1, v2, v3
	s_nop 0
	global_store_dwordx2 v128, v[0:1], s[18:19]
	s_waitcnt vmcnt(5)
	v_pk_mul_f32 v[144:145], v[144:145], v[150:151] op_sel_hi:[1,0]
	v_pk_mul_f32 v[146:147], v[146:147], v[150:151] op_sel_hi:[1,0]
	v_pk_fma_f32 v[4:5], v[140:141], v[144:145], v[132:133]
	v_pk_fma_f32 v[6:7], v[142:143], v[146:147], v[134:135]
	v_pk_mul_f32 v[10:11], v[4:5], v[4:5]
	v_pk_mul_f32 v[8:9], v[6:7], v[6:7]
	v_pk_fma_f32 v[10:11], v[10:11], s[12:13], v[16:17] op_sel_hi:[1,0,0] neg_lo:[1,0,0] neg_hi:[1,0,0]
	v_pk_fma_f32 v[8:9], v[8:9], s[12:13], v[16:17] op_sel_hi:[1,0,0] neg_lo:[1,0,0] neg_hi:[1,0,0]
	v_pk_mul_f32 v[10:11], v[4:5], v[10:11]
	v_pk_mul_f32 v[8:9], v[6:7], v[8:9]
	v_exp_f32_e32 v10, v10
	v_exp_f32_e32 v11, v11
	v_exp_f32_e32 v8, v8
	v_exp_f32_e32 v9, v9
	s_nop 0
	v_pk_add_f32 v[10:11], v[10:11], 1.0 op_sel_hi:[1,0]
	v_pk_add_f32 v[8:9], v[8:9], 1.0 op_sel_hi:[1,0]
	v_rcp_f32_e32 v10, v10
	v_rcp_f32_e32 v11, v11
	v_rcp_f32_e32 v8, v8
	v_rcp_f32_e32 v9, v9
	s_nop 0
	v_pk_mul_f32 v[4:5], v[4:5], v[10:11]
	v_pk_mul_f32 v[6:7], v[6:7], v[8:9]
	v_pk_mul_f32 v[0:1], v[136:137], v[4:5]
	v_pk_mul_f32 v[2:3], v[138:139], v[6:7]
	s_nop 0
	v_cvt_pk_bf16_f32 v0, v0, v1
	v_cvt_pk_bf16_f32 v1, v2, v3
	s_nop 0
	v_cmp_gt_u32_e32 vcc, s24, v24
	s_nop 1
	s_and_saveexec_b64 s[20:21], vcc
	global_store_dwordx2 v148, v[0:1], s[18:19]
	s_or_b64 exec, exec, s[20:21]
	s_branch .LBB0_666
